# attention row-sum chain: packed f32 adds replaced by scalar adds (same order)
# speedup vs baseline: 1.0192x; 1.0192x over previous
.LBB0_1364:
	s_sub_i32 s12, 4, s73
	v_cvt_f32_u32_e32 v4, s12
	v_mad_u32_u24 v2, v218, s78, 0
	v_lshlrev_b32_e32 v5, 7, v218
	v_lshl_add_u32 v3, s70, 7, v2
	v_sub_u32_e32 v2, v2, v5
	v_add_u32_e32 v221, v2, v194
	v_mul_f32_e32 v2, -2.0, v4
	v_cmp_gt_f32_e32 vcc, s89, v2
	s_and_b64 s[12:13], vcc, exec
	s_cselect_b32 s12, 0xffffffc0, 0
	v_cndmask_b32_e32 v2, 0, v215, vcc
	v_fmac_f32_e32 v2, -2.0, v4
	v_exp_f32_e32 v2, v2
	v_add_u32_e32 v200, s74, v218
	v_mul_i32_i24_e32 v227, -4, v219
	v_add_u32_e32 v222, v3, v194
	v_ldexp_f32 v2, v2, s12
	s_lshl_b32 s12, s46, 1
	s_sub_i32 s12, s71, s12
	v_mul_f32_e32 v201, 0x3fb8aa3b, v2
	s_cmp_lt_i32 s12, 1
	v_add_u32_e32 v223, v200, v227
	s_cbranch_scc1 .LBB0_1366
	ds_read_b128 v[2:5], v222
	ds_read_b128 v[34:37], v222 offset:32
	ds_read_b128 v[6:9], v222 offset:8704
	ds_read_b128 v[38:41], v222 offset:8736
	ds_read_b128 v[42:45], v222 offset:64
	ds_read_b128 v[46:49], v222 offset:96
	ds_read_b128 v[50:53], v222 offset:8768
	ds_read_b128 v[54:57], v222 offset:8800
	s_waitcnt lgkmcnt(7)
	v_mfma_f32_32x32x16_bf16 v[18:33], v[2:5], v[130:133], 0
	s_waitcnt lgkmcnt(5)
	v_mfma_f32_32x32x16_bf16 v[2:17], v[6:9], v[130:133], 0
	v_mfma_f32_32x32x16_bf16 v[18:33], v[34:37], v[134:137], v[18:33]
	ds_read_b128 v[34:37], v221 offset:17408
	ds_read_b128 v[66:69], v221 offset:17440
	ds_read_b128 v[82:85], v221 offset:22016
	ds_read_b128 v[70:73], v221 offset:22048
	ds_read_b128 v[86:89], v221 offset:26624
	ds_read_b128 v[74:77], v221 offset:26656
	ds_read_b128 v[90:93], v221 offset:31232
	ds_read_b128 v[78:81], v221 offset:31264
	s_waitcnt lgkmcnt(12)
	v_mfma_f32_32x32x16_bf16 v[2:17], v[38:41], v[134:137], v[2:17]
	s_waitcnt lgkmcnt(11)
	v_mfma_f32_32x32x16_bf16 v[18:33], v[42:45], v[138:141], v[18:33]
	s_waitcnt lgkmcnt(9)
	v_mfma_f32_32x32x16_bf16 v[2:17], v[50:53], v[138:141], v[2:17]
	v_mfma_f32_32x32x16_bf16 v[18:33], v[46:49], v[142:145], v[18:33]
	s_waitcnt lgkmcnt(8)
	v_mfma_f32_32x32x16_bf16 v[2:17], v[54:57], v[142:145], v[2:17]
	v_add_u32_e32 v38, v200, v227
	s_lshl_b32 s13, s46, 6
	v_subrev_u32_e32 v38, s13, v38
	v_cvt_f32_i32_e32 v38, v38
	s_cmp_eq_u32 s12, 1
	v_add_f32_e32 v39, 0xc2000000, v38
	v_add_f32_e32 v41, -1.0, v38
	s_nop 2
	v_fma_f32 v19, -v201, |v41|, v19
	v_add_f32_e32 v41, -1.0, v39
	v_fma_f32 v2, -v201, |v39|, v2
	s_cselect_b64 vcc, -1, 0
	v_fma_f32 v3, -v201, |v41|, v3
	v_fma_f32 v18, -v201, |v38|, v18
	v_cndmask_b32_e32 v40, v2, v216, vcc
	v_cndmask_b32_e32 v3, v3, v216, vcc
	v_max_f32_e32 v2, v18, v40
	v_max_f32_e32 v41, v19, v3
	v_max3_f32 v2, v2, s42, v41
	v_add_f32_e32 v41, -2.0, v38
	v_fma_f32 v41, -v201, |v41|, v20
	v_add_f32_e32 v20, -2.0, v39
	v_fma_f32 v4, -v201, |v20|, v4
	v_add_f32_e32 v20, 0xc0400000, v38
	v_fma_f32 v43, -v201, |v20|, v21
	v_add_f32_e32 v20, 0xc0400000, v39
	v_fma_f32 v5, -v201, |v20|, v5
	v_cndmask_b32_e32 v42, v4, v216, vcc
	v_cndmask_b32_e32 v44, v5, v216, vcc
	v_max_f32_e32 v4, v41, v42
	v_max_f32_e32 v5, v43, v44
	v_max3_f32 v2, v2, v4, v5
	v_add_f32_e32 v4, 0xc1000000, v38
	v_add_f32_e32 v5, 0xc1100000, v38
	v_fma_f32 v45, -v201, |v4|, v22
	v_add_f32_e32 v4, 0xc1000000, v39
	v_fma_f32 v47, -v201, |v5|, v23
	v_add_f32_e32 v5, 0xc1100000, v39
	v_fma_f32 v4, -v201, |v4|, v6
	v_fma_f32 v5, -v201, |v5|, v7
	v_cndmask_b32_e32 v46, v4, v216, vcc
	v_cndmask_b32_e32 v48, v5, v216, vcc
	v_max_f32_e32 v4, v45, v46
	v_max_f32_e32 v5, v47, v48
	v_max3_f32 v2, v2, v4, v5
	v_add_f32_e32 v4, 0xc1200000, v38
	v_add_f32_e32 v5, 0xc1300000, v38
	v_fma_f32 v49, -v201, |v4|, v24
	v_add_f32_e32 v4, 0xc1200000, v39
	v_fma_f32 v51, -v201, |v5|, v25
	v_add_f32_e32 v5, 0xc1300000, v39
	v_fma_f32 v4, -v201, |v4|, v8
	v_fma_f32 v5, -v201, |v5|, v9
	v_cndmask_b32_e32 v50, v4, v216, vcc
	v_cndmask_b32_e32 v52, v5, v216, vcc
	v_max_f32_e32 v4, v49, v50
	v_max_f32_e32 v5, v51, v52
	v_max3_f32 v2, v2, v4, v5
	v_add_f32_e32 v4, 0xc1800000, v38
	v_add_f32_e32 v5, 0xc1880000, v38
	v_fma_f32 v53, -v201, |v4|, v26
	v_add_f32_e32 v4, 0xc1800000, v39
	v_fma_f32 v55, -v201, |v5|, v27
	v_add_f32_e32 v5, 0xc1880000, v39
	v_fma_f32 v4, -v201, |v4|, v10
	v_fma_f32 v5, -v201, |v5|, v11
	v_cndmask_b32_e32 v54, v4, v216, vcc
	v_cndmask_b32_e32 v56, v5, v216, vcc
	v_max_f32_e32 v4, v53, v54
	v_max_f32_e32 v5, v55, v56
	v_max3_f32 v2, v2, v4, v5
	v_add_f32_e32 v4, 0xc1900000, v38
	v_add_f32_e32 v5, 0xc1980000, v38
	v_fma_f32 v57, -v201, |v4|, v28
	v_add_f32_e32 v4, 0xc1900000, v39
	v_fma_f32 v59, -v201, |v5|, v29
	v_add_f32_e32 v5, 0xc1980000, v39
	v_fma_f32 v4, -v201, |v4|, v12
	v_fma_f32 v5, -v201, |v5|, v13
	v_cndmask_b32_e32 v58, v4, v216, vcc
	v_cndmask_b32_e32 v60, v5, v216, vcc
	v_max_f32_e32 v4, v57, v58
	v_max_f32_e32 v5, v59, v60
	v_max3_f32 v2, v2, v4, v5
	v_add_f32_e32 v4, 0xc1c00000, v38
	v_add_f32_e32 v5, 0xc1c80000, v38
	v_fma_f32 v61, -v201, |v4|, v30
	v_add_f32_e32 v4, 0xc1c00000, v39
	v_fma_f32 v63, -v201, |v5|, v31
	v_add_f32_e32 v5, 0xc1c80000, v39
	v_fma_f32 v4, -v201, |v4|, v14
	v_fma_f32 v5, -v201, |v5|, v15
	v_cndmask_b32_e32 v62, v4, v216, vcc
	v_cndmask_b32_e32 v64, v5, v216, vcc
	v_max_f32_e32 v4, v61, v62
	v_max_f32_e32 v5, v63, v64
	v_max3_f32 v2, v2, v4, v5
	v_add_f32_e32 v4, 0xc1d00000, v38
	v_add_f32_e32 v5, 0xc1d80000, v38
	v_fma_f32 v65, -v201, |v4|, v32
	v_add_f32_e32 v4, 0xc1d00000, v39
	v_fma_f32 v95, -v201, |v5|, v33
	v_add_f32_e32 v5, 0xc1d80000, v39
	v_fma_f32 v4, -v201, |v4|, v16
	v_fma_f32 v5, -v201, |v5|, v17
	v_cndmask_b32_e32 v94, v4, v216, vcc
	v_cndmask_b32_e32 v96, v5, v216, vcc
	v_max_f32_e32 v4, v65, v94
	v_max_f32_e32 v5, v95, v96
	v_max3_f32 v2, v2, v4, v5
	ds_bpermute_b32 v4, v1, v2
	s_waitcnt lgkmcnt(0)
	v_max_f32_e32 v4, v4, v4
	v_max_f32_e32 v2, v2, v4
	v_cmp_lt_f32_e32 vcc, s42, v2
	s_cmp_eq_u64 vcc, 0
	v_max_f32_e32 v4, 0xf149f2ca, v2
	s_cselect_b64 vcc, -1, 0
	v_cndmask_b32_e32 v226, v4, v216, vcc
	v_sub_f32_e32 v5, 0xf149f2ca, v4
	v_sub_f32_e32 v4, v18, v226
	v_exp_f32_e32 v97, v4
	v_sub_f32_e32 v4, v40, v226
	v_exp_f32_e32 v154, v4
	v_sub_f32_e32 v4, v19, v226
	v_sub_f32_e32 v3, v3, v226
	v_exp_f32_e32 v5, v5
	v_exp_f32_e32 v18, v4
	v_exp_f32_e32 v188, v3
	v_add_f32_e32 v19, v97, v154
	v_mul_f32_e32 v2, 0, v5
	v_cndmask_b32_e64 v2, v2, 0, vcc
	v_add_f32_e32 v4, v18, v188
	v_add_f32_e32 v5, v19, v189
	v_mov_b32_e32 v3, v2
	v_add_f32_e32 v21, v4, v5
	v_sub_f32_e32 v4, v41, v226
	v_exp_f32_e32 v19, v4
	v_sub_f32_e32 v4, v42, v226
	v_exp_f32_e32 v155, v4
	v_sub_f32_e32 v4, v43, v226
	v_exp_f32_e32 v22, v4
	v_sub_f32_e32 v4, v44, v226
	v_exp_f32_e32 v20, v4
	v_add_f32_e32 v23, v19, v155
	v_mov_b32_e32 v4, v2
	v_mov_b32_e32 v5, v2
	v_add_f32_e32 v6, v22, v20
	v_add_f32_e32 v7, v23, v21
	v_cvt_pk_bf16_f32 v154, v154, v188
	v_add_f32_e32 v25, v6, v7
	v_sub_f32_e32 v6, v45, v226
	v_exp_f32_e32 v21, v6
	v_sub_f32_e32 v6, v46, v226
	v_exp_f32_e32 v23, v6
	v_sub_f32_e32 v6, v47, v226
	v_exp_f32_e32 v26, v6
	v_sub_f32_e32 v6, v48, v226
	v_exp_f32_e32 v24, v6
	v_add_f32_e32 v27, v21, v23
	v_mov_b32_e32 v6, v2
	v_mov_b32_e32 v7, v2
	v_add_f32_e32 v8, v26, v24
	v_add_f32_e32 v9, v27, v25
	v_cvt_pk_bf16_f32 v155, v155, v20
	v_add_f32_e32 v29, v8, v9
	v_sub_f32_e32 v8, v49, v226
	v_exp_f32_e32 v25, v8
	v_sub_f32_e32 v8, v50, v226
	v_exp_f32_e32 v27, v8
	v_sub_f32_e32 v8, v51, v226
	v_exp_f32_e32 v30, v8
	v_sub_f32_e32 v8, v52, v226
	v_exp_f32_e32 v28, v8
	v_add_f32_e32 v31, v25, v27
	v_mov_b32_e32 v8, v2
	v_mov_b32_e32 v9, v2
	v_add_f32_e32 v10, v30, v28
	v_add_f32_e32 v11, v31, v29
	v_cvt_pk_bf16_f32 v156, v23, v24
	v_add_f32_e32 v33, v10, v11
	v_sub_f32_e32 v10, v53, v226
	v_exp_f32_e32 v29, v10
	v_sub_f32_e32 v10, v54, v226
	v_exp_f32_e32 v31, v10
	v_sub_f32_e32 v10, v55, v226
	v_exp_f32_e32 v38, v10
	v_sub_f32_e32 v10, v56, v226
	v_exp_f32_e32 v32, v10
	v_add_f32_e32 v39, v29, v31
	v_mov_b32_e32 v10, v2
	v_mov_b32_e32 v11, v2
	v_add_f32_e32 v12, v38, v32
	v_add_f32_e32 v13, v39, v33
	v_cvt_pk_bf16_f32 v157, v27, v28
	v_add_f32_e32 v41, v12, v13
	v_sub_f32_e32 v12, v57, v226
	v_exp_f32_e32 v33, v12
	v_sub_f32_e32 v12, v58, v226
	v_exp_f32_e32 v39, v12
	v_sub_f32_e32 v12, v59, v226
	v_exp_f32_e32 v42, v12
	v_sub_f32_e32 v12, v60, v226
	v_exp_f32_e32 v40, v12
	v_add_f32_e32 v43, v33, v39
	v_mov_b32_e32 v12, v2
	v_mov_b32_e32 v13, v2
	v_add_f32_e32 v14, v42, v40
	v_add_f32_e32 v15, v43, v41
	v_cvt_pk_bf16_f32 v158, v29, v38
	v_add_f32_e32 v45, v14, v15
	v_sub_f32_e32 v14, v61, v226
	v_exp_f32_e32 v41, v14
	v_sub_f32_e32 v14, v62, v226
	v_exp_f32_e32 v43, v14
	v_sub_f32_e32 v14, v63, v226
	v_exp_f32_e32 v46, v14
	v_sub_f32_e32 v14, v64, v226
	v_exp_f32_e32 v44, v14
	v_add_f32_e32 v47, v41, v43
	v_mov_b32_e32 v14, v2
	v_mov_b32_e32 v15, v2
	v_add_f32_e32 v16, v46, v44
	v_add_f32_e32 v17, v47, v45
	v_cvt_pk_bf16_f32 v159, v33, v42
	v_add_f32_e32 v49, v16, v17
	v_sub_f32_e32 v16, v65, v226
	v_exp_f32_e32 v45, v16
	v_sub_f32_e32 v16, v94, v226
	v_exp_f32_e32 v47, v16
	v_sub_f32_e32 v16, v95, v226
	v_exp_f32_e32 v50, v16
	v_sub_f32_e32 v16, v96, v226
	v_exp_f32_e32 v48, v16
	v_add_f32_e32 v51, v45, v47
	v_mov_b32_e32 v16, v2
	v_mov_b32_e32 v17, v2
	v_add_f32_e32 v52, v50, v48
	v_add_f32_e32 v53, v51, v49
	v_cvt_pk_bf16_f32 v94, v97, v18
	v_add_f32_e32 v49, v52, v53
	v_add_f32_e32 v224, v2, v49
	v_cvt_pk_bf16_f32 v95, v19, v22
	v_cvt_pk_bf16_f32 v96, v21, v26
	v_cvt_pk_bf16_f32 v97, v25, v30
	v_cvt_pk_bf16_f32 v160, v41, v46
	v_cvt_pk_bf16_f32 v161, v45, v50
	v_cvt_pk_bf16_f32 v162, v31, v32
	v_cvt_pk_bf16_f32 v163, v39, v40
	v_cvt_pk_bf16_f32 v164, v43, v44
	v_cvt_pk_bf16_f32 v165, v47, v48
	ds_read_b128 v[166:169], v221 offset:17472
	ds_read_b128 v[170:173], v221 offset:17504
	ds_read_b128 v[174:177], v221 offset:22080
	ds_read_b128 v[178:181], v221 offset:22112
	ds_read_b128 v[182:185], v221 offset:26688
	ds_read_b128 v[228:231], v221 offset:26720
	ds_read_b128 v[232:235], v221 offset:31296
	ds_read_b128 v[236:239], v221 offset:31328
	v_mfma_f32_32x32x16_bf16 v[50:65], v[34:37], v[94:97], v[2:17]
	v_mfma_f32_32x32x16_bf16 v[34:49], v[82:85], v[94:97], v[2:17]
	v_mfma_f32_32x32x16_bf16 v[18:33], v[86:89], v[94:97], v[2:17]
	v_mfma_f32_32x32x16_bf16 v[2:17], v[90:93], v[94:97], v[2:17]
	v_mfma_f32_32x32x16_bf16 v[50:65], v[66:69], v[158:161], v[50:65]
	v_mfma_f32_32x32x16_bf16 v[34:49], v[70:73], v[158:161], v[34:49]
	v_mfma_f32_32x32x16_bf16 v[18:33], v[74:77], v[158:161], v[18:33]
	v_mfma_f32_32x32x16_bf16 v[2:17], v[78:81], v[158:161], v[2:17]
	s_waitcnt lgkmcnt(7)
	v_mfma_f32_32x32x16_bf16 v[50:65], v[166:169], v[154:157], v[50:65]
	s_waitcnt lgkmcnt(5)
	v_mfma_f32_32x32x16_bf16 v[34:49], v[174:177], v[154:157], v[34:49]
	s_waitcnt lgkmcnt(3)
	v_mfma_f32_32x32x16_bf16 v[18:33], v[182:185], v[154:157], v[18:33]
	s_waitcnt lgkmcnt(1)
	v_mfma_f32_32x32x16_bf16 v[2:17], v[232:235], v[154:157], v[2:17]
	v_mfma_f32_32x32x16_bf16 v[50:65], v[170:173], v[162:165], v[50:65]
	v_mfma_f32_32x32x16_bf16 v[34:49], v[178:181], v[162:165], v[34:49]
	v_mfma_f32_32x32x16_bf16 v[18:33], v[228:231], v[162:165], v[18:33]
	s_waitcnt lgkmcnt(0)
	v_mfma_f32_32x32x16_bf16 v[2:17], v[236:239], v[162:165], v[2:17]
	s_branch .LBB0_1367

.LBB0_1372:
	v_sub_f32_e32 v78, v188, v226
	v_exp_f32_e32 v237, v78
	v_sub_f32_e32 v78, v234, v226
	v_exp_f32_e32 v238, v78
	v_sub_f32_e32 v78, v235, v226
	v_sub_f32_e32 v79, v236, v226
	v_exp_f32_e32 v78, v78
	v_exp_f32_e32 v188, v79
	v_add_f32_e32 v79, v237, v238
	v_sub_f32_e32 v86, v86, v226
	v_sub_f32_e32 v82, v82, v226
	v_add_f32_e32 v80, v78, v188
	v_add_f32_e32 v81, v79, v189
	v_sub_f32_e32 v79, v230, v226
	v_add_f32_e32 v81, v80, v81
	v_sub_f32_e32 v80, v231, v226
	v_exp_f32_e32 v236, v80
	v_sub_f32_e32 v80, v232, v226
	v_exp_f32_e32 v79, v79
	v_exp_f32_e32 v90, v80
	v_sub_f32_e32 v80, v233, v226
	v_exp_f32_e32 v80, v80
	v_add_f32_e32 v91, v79, v236
	v_sub_f32_e32 v74, v74, v226
	v_sub_f32_e32 v70, v70, v226
	v_add_f32_e32 v92, v90, v80
	v_add_f32_e32 v93, v91, v81
	v_sub_f32_e32 v81, v200, v226
	v_add_f32_e32 v93, v92, v93
	v_sub_f32_e32 v91, v227, v226
	v_sub_f32_e32 v92, v228, v226
	v_exp_f32_e32 v81, v81
	v_exp_f32_e32 v91, v91
	v_exp_f32_e32 v94, v92
	v_sub_f32_e32 v92, v229, v226
	v_exp_f32_e32 v92, v92
	v_add_f32_e32 v95, v81, v91
	v_sub_f32_e32 v66, v66, v226
	v_exp_f32_e32 v200, v66
	v_add_f32_e32 v96, v94, v92
	v_add_f32_e32 v97, v95, v93
	v_exp_f32_e32 v93, v86
	v_sub_f32_e32 v86, v87, v226
	v_add_f32_e32 v97, v96, v97
	v_exp_f32_e32 v95, v86
	v_sub_f32_e32 v86, v88, v226
	v_sub_f32_e32 v87, v89, v226
	v_exp_f32_e32 v86, v86
	v_exp_f32_e32 v96, v87
	v_add_f32_e32 v87, v93, v95
	v_sub_f32_e32 v66, v67, v226
	v_exp_f32_e32 v227, v66
	v_add_f32_e32 v88, v86, v96
	v_add_f32_e32 v89, v87, v97
	v_exp_f32_e32 v87, v82
	v_sub_f32_e32 v82, v83, v226
	v_add_f32_e32 v89, v88, v89
	v_exp_f32_e32 v97, v82
	v_sub_f32_e32 v82, v84, v226
	v_sub_f32_e32 v83, v85, v226
	v_exp_f32_e32 v82, v82
	v_exp_f32_e32 v88, v83
	v_add_f32_e32 v83, v87, v97
	v_sub_f32_e32 v66, v68, v226
	v_exp_f32_e32 v234, v66
	v_add_f32_e32 v84, v82, v88
	v_add_f32_e32 v85, v83, v89
	v_exp_f32_e32 v83, v74
	v_sub_f32_e32 v74, v75, v226
	v_exp_f32_e32 v89, v74
	v_sub_f32_e32 v74, v76, v226
	v_add_f32_e32 v85, v84, v85
	v_exp_f32_e32 v76, v74
	v_sub_f32_e32 v74, v77, v226
	v_exp_f32_e32 v84, v74
	v_add_f32_e32 v77, v83, v89
	v_sub_f32_e32 v66, v69, v226
	v_add_f32_e32 v235, v200, v227
	v_add_f32_e32 v74, v76, v84
	v_add_f32_e32 v75, v77, v85
	v_exp_f32_e32 v77, v70
	v_sub_f32_e32 v70, v71, v226
	v_exp_f32_e32 v85, v70
	v_sub_f32_e32 v70, v72, v226
	v_add_f32_e32 v229, v74, v75
	v_exp_f32_e32 v230, v70
	v_sub_f32_e32 v70, v73, v226
	v_exp_f32_e32 v228, v70
	v_add_f32_e32 v231, v77, v85
	v_cvt_pk_bf16_f32 v68, v81, v94
	v_cvt_pk_bf16_f32 v69, v93, v86
	v_add_f32_e32 v70, v230, v228
	v_add_f32_e32 v71, v231, v229
	v_cvt_pk_bf16_f32 v72, v91, v92
	v_add_f32_e32 v233, v70, v71
	v_exp_f32_e32 v232, v66
	v_cvt_pk_bf16_f32 v70, v238, v188
	v_cvt_pk_bf16_f32 v71, v236, v80
	v_cvt_pk_bf16_f32 v73, v95, v96
	v_add_f32_e32 v66, v234, v232
	v_add_f32_e32 v67, v235, v233
	v_cvt_pk_bf16_f32 v74, v87, v82
	v_add_f32_e32 v66, v66, v67
	v_add_f32_e32 v224, v224, v66
	v_cvt_pk_bf16_f32 v66, v237, v78
	v_cvt_pk_bf16_f32 v67, v79, v90
	v_cvt_pk_bf16_f32 v75, v83, v76
	v_cvt_pk_bf16_f32 v76, v77, v230
	v_cvt_pk_bf16_f32 v77, v200, v234
	v_cvt_pk_bf16_f32 v78, v97, v88
	v_cvt_pk_bf16_f32 v79, v89, v84
	v_cvt_pk_bf16_f32 v80, v85, v228
	v_cvt_pk_bf16_f32 v81, v227, v232
	ds_read_b128 v[82:85], v221 offset:53312
	ds_read_b128 v[86:89], v221 offset:53344
	ds_read_b128 v[90:93], v221 offset:57920
	ds_read_b128 v[94:97], v221 offset:57952
	ds_read_b128 v[228:231], v221 offset:62528
	ds_read_b128 v[232:235], v221 offset:62560
	ds_read_b128 v[236:239], v225 offset:13888
	ds_read_b128 v[240:243], v225 offset:13920
	v_mfma_f32_32x32x16_bf16 v[50:65], v[174:177], v[66:69], v[50:65]
	v_mfma_f32_32x32x16_bf16 v[34:49], v[178:181], v[66:69], v[34:49]
	v_mfma_f32_32x32x16_bf16 v[18:33], v[182:185], v[66:69], v[18:33]
	v_mfma_f32_32x32x16_bf16 v[2:17], v[170:173], v[66:69], v[2:17]
	v_mfma_f32_32x32x16_bf16 v[50:65], v[158:161], v[74:77], v[50:65]
	v_mfma_f32_32x32x16_bf16 v[34:49], v[162:165], v[74:77], v[34:49]
	v_mfma_f32_32x32x16_bf16 v[18:33], v[166:169], v[74:77], v[18:33]
	v_mfma_f32_32x32x16_bf16 v[2:17], v[154:157], v[74:77], v[2:17]
	s_waitcnt lgkmcnt(7)
	v_mfma_f32_32x32x16_bf16 v[50:65], v[82:85], v[70:73], v[50:65]
	s_waitcnt lgkmcnt(5)
	v_mfma_f32_32x32x16_bf16 v[34:49], v[90:93], v[70:73], v[34:49]
	s_waitcnt lgkmcnt(3)
	v_mfma_f32_32x32x16_bf16 v[18:33], v[228:231], v[70:73], v[18:33]
	s_waitcnt lgkmcnt(1)
	v_mfma_f32_32x32x16_bf16 v[2:17], v[236:239], v[70:73], v[2:17]
	v_mfma_f32_32x32x16_bf16 v[50:65], v[86:89], v[78:81], v[50:65]
	v_mfma_f32_32x32x16_bf16 v[34:49], v[94:97], v[78:81], v[34:49]
	v_mfma_f32_32x32x16_bf16 v[18:33], v[232:235], v[78:81], v[18:33]
	s_waitcnt lgkmcnt(0)
	v_mfma_f32_32x32x16_bf16 v[2:17], v[240:243], v[78:81], v[2:17]

.LBB0_1387:
	v_sub_f32_e32 v246, v226, v245
	v_sub_f32_e32 v78, v188, v246
	v_exp_f32_e32 v236, v78
	v_sub_f32_e32 v78, v233, v246
	v_exp_f32_e32 v237, v78
	v_sub_f32_e32 v78, v234, v246
	v_sub_f32_e32 v79, v235, v246
	v_exp_f32_e32 v78, v78
	v_exp_f32_e32 v188, v79
	v_add_f32_e32 v79, v236, v237
	v_sub_f32_e32 v86, v86, v246
	v_sub_f32_e32 v82, v82, v246
	v_add_f32_e32 v80, v78, v188
	v_add_f32_e32 v81, v79, v189
	v_sub_f32_e32 v79, v229, v246
	v_add_f32_e32 v81, v80, v81
	v_sub_f32_e32 v80, v230, v246
	v_exp_f32_e32 v234, v80
	v_sub_f32_e32 v80, v231, v246
	v_exp_f32_e32 v79, v79
	v_exp_f32_e32 v90, v80
	v_sub_f32_e32 v80, v232, v246
	v_exp_f32_e32 v80, v80
	v_add_f32_e32 v91, v79, v234
	v_sub_f32_e32 v74, v74, v246
	v_sub_f32_e32 v70, v70, v246
	v_add_f32_e32 v92, v90, v80
	v_add_f32_e32 v93, v91, v81
	v_sub_f32_e32 v81, v184, v246
	v_add_f32_e32 v93, v92, v93
	v_sub_f32_e32 v91, v185, v246
	v_sub_f32_e32 v92, v227, v246
	v_exp_f32_e32 v81, v81
	v_exp_f32_e32 v91, v91
	v_exp_f32_e32 v94, v92
	v_sub_f32_e32 v92, v228, v246
	v_exp_f32_e32 v92, v92
	v_add_f32_e32 v95, v81, v91
	v_sub_f32_e32 v66, v66, v246
	v_add_f32_e32 v96, v94, v92
	v_add_f32_e32 v97, v95, v93
	v_exp_f32_e32 v93, v86
	v_sub_f32_e32 v86, v87, v246
	v_add_f32_e32 v97, v96, v97
	v_exp_f32_e32 v95, v86
	v_sub_f32_e32 v86, v88, v246
	v_sub_f32_e32 v87, v89, v246
	v_exp_f32_e32 v86, v86
	v_exp_f32_e32 v96, v87
	v_add_f32_e32 v87, v93, v95
	v_add_f32_e32 v88, v86, v96
	v_add_f32_e32 v89, v87, v97
	v_exp_f32_e32 v87, v82
	v_sub_f32_e32 v82, v83, v246
	v_add_f32_e32 v89, v88, v89
	v_exp_f32_e32 v97, v82
	v_sub_f32_e32 v82, v84, v246
	v_sub_f32_e32 v83, v85, v246
	v_exp_f32_e32 v82, v82
	v_exp_f32_e32 v88, v83
	v_add_f32_e32 v83, v87, v97
	v_add_f32_e32 v84, v82, v88
	v_add_f32_e32 v85, v83, v89
	v_exp_f32_e32 v83, v74
	v_sub_f32_e32 v74, v75, v246
	v_exp_f32_e32 v89, v74
	v_sub_f32_e32 v74, v76, v246
	v_add_f32_e32 v85, v84, v85
	v_exp_f32_e32 v76, v74
	v_sub_f32_e32 v74, v77, v246
	v_exp_f32_e32 v84, v74
	v_add_f32_e32 v77, v83, v89
	v_add_f32_e32 v74, v76, v84
	v_add_f32_e32 v75, v77, v85
	v_exp_f32_e32 v77, v70
	v_sub_f32_e32 v70, v71, v246
	v_exp_f32_e32 v85, v70
	v_sub_f32_e32 v70, v72, v246
	v_add_f32_e32 v185, v74, v75
	v_exp_f32_e32 v228, v70
	v_sub_f32_e32 v70, v73, v246
	v_exp_f32_e32 v184, v70
	v_add_f32_e32 v229, v77, v85
	v_cvt_pk_bf16_f32 v72, v91, v92
	v_cvt_pk_bf16_f32 v73, v95, v96
	v_add_f32_e32 v70, v228, v184
	v_add_f32_e32 v71, v229, v185
	v_exp_f32_e32 v185, v66
	v_sub_f32_e32 v66, v67, v246
	v_exp_f32_e32 v227, v66
	v_sub_f32_e32 v66, v68, v246
	v_add_f32_e32 v231, v70, v71
	v_exp_f32_e32 v232, v66
	v_sub_f32_e32 v66, v69, v246
	v_exp_f32_e32 v230, v66
	v_add_f32_e32 v233, v185, v227
	v_cvt_pk_bf16_f32 v68, v81, v94
	v_cvt_pk_bf16_f32 v69, v93, v86
	v_add_f32_e32 v66, v232, v230
	v_add_f32_e32 v67, v233, v231
	v_cvt_pk_bf16_f32 v70, v237, v188
	v_add_f32_e32 v66, v66, v67
	v_add_f32_e32 v224, v224, v66
	v_cvt_pk_bf16_f32 v66, v236, v78
	v_cvt_pk_bf16_f32 v67, v79, v90
	v_cvt_pk_bf16_f32 v71, v234, v80
	v_cvt_pk_bf16_f32 v74, v87, v82
	v_cvt_pk_bf16_f32 v75, v83, v76
	v_cvt_pk_bf16_f32 v76, v77, v228
	v_cvt_pk_bf16_f32 v77, v185, v232
	v_cvt_pk_bf16_f32 v78, v97, v88
	v_cvt_pk_bf16_f32 v79, v89, v84
	v_cvt_pk_bf16_f32 v80, v85, v184
	v_cvt_pk_bf16_f32 v81, v227, v230
	ds_read_b128 v[82:85], v221 offset:17472
	ds_read_b128 v[86:89], v221 offset:17504
	ds_read_b128 v[90:93], v221 offset:22080
	ds_read_b128 v[94:97], v221 offset:22112
	ds_read_b128 v[228:231], v221 offset:26688
	ds_read_b128 v[232:235], v221 offset:26720
	ds_read_b128 v[236:239], v221 offset:31296
	ds_read_b128 v[240:243], v221 offset:31328
	v_mfma_f32_32x32x16_bf16 v[50:65], v[162:165], v[66:69], v[50:65]
	v_mfma_f32_32x32x16_bf16 v[34:49], v[166:169], v[66:69], v[34:49]
	v_mfma_f32_32x32x16_bf16 v[18:33], v[170:173], v[66:69], v[18:33]
	v_mfma_f32_32x32x16_bf16 v[2:17], v[174:177], v[66:69], v[2:17]
	v_mfma_f32_32x32x16_bf16 v[50:65], v[146:149], v[74:77], v[50:65]
	v_mfma_f32_32x32x16_bf16 v[34:49], v[150:153], v[74:77], v[34:49]
	v_mfma_f32_32x32x16_bf16 v[18:33], v[154:157], v[74:77], v[18:33]
	v_mfma_f32_32x32x16_bf16 v[2:17], v[158:161], v[74:77], v[2:17]
	s_waitcnt lgkmcnt(7)
	v_mfma_f32_32x32x16_bf16 v[50:65], v[82:85], v[70:73], v[50:65]
	s_waitcnt lgkmcnt(5)
	v_mfma_f32_32x32x16_bf16 v[34:49], v[90:93], v[70:73], v[34:49]
	s_waitcnt lgkmcnt(3)
	v_mfma_f32_32x32x16_bf16 v[18:33], v[228:231], v[70:73], v[18:33]
	s_waitcnt lgkmcnt(1)
	v_mfma_f32_32x32x16_bf16 v[2:17], v[236:239], v[70:73], v[2:17]
	v_mfma_f32_32x32x16_bf16 v[50:65], v[86:89], v[78:81], v[50:65]
	v_mfma_f32_32x32x16_bf16 v[34:49], v[94:97], v[78:81], v[34:49]
	v_mfma_f32_32x32x16_bf16 v[18:33], v[232:235], v[78:81], v[18:33]
	s_waitcnt lgkmcnt(0)
	v_mfma_f32_32x32x16_bf16 v[2:17], v[240:243], v[78:81], v[2:17]

.LBB0_1400:
	v_sub_f32_e32 v246, v226, v245
	v_sub_f32_e32 v78, v188, v246
	v_exp_f32_e32 v236, v78
	v_sub_f32_e32 v78, v233, v246
	v_exp_f32_e32 v237, v78
	v_sub_f32_e32 v78, v234, v246
	v_sub_f32_e32 v79, v235, v246
	v_exp_f32_e32 v78, v78
	v_exp_f32_e32 v188, v79
	v_add_f32_e32 v79, v236, v237
	v_sub_f32_e32 v86, v86, v246
	v_sub_f32_e32 v82, v82, v246
	v_add_f32_e32 v80, v78, v188
	v_add_f32_e32 v81, v79, v189
	v_sub_f32_e32 v79, v229, v246
	v_add_f32_e32 v81, v80, v81
	v_sub_f32_e32 v80, v230, v246
	v_exp_f32_e32 v234, v80
	v_sub_f32_e32 v80, v231, v246
	v_exp_f32_e32 v79, v79
	v_exp_f32_e32 v90, v80
	v_sub_f32_e32 v80, v232, v246
	v_exp_f32_e32 v80, v80
	v_add_f32_e32 v91, v79, v234
	v_sub_f32_e32 v74, v74, v246
	v_sub_f32_e32 v70, v70, v246
	v_add_f32_e32 v92, v90, v80
	v_add_f32_e32 v93, v91, v81
	v_sub_f32_e32 v81, v184, v246
	v_add_f32_e32 v93, v92, v93
	v_sub_f32_e32 v91, v185, v246
	v_sub_f32_e32 v92, v227, v246
	v_exp_f32_e32 v81, v81
	v_exp_f32_e32 v91, v91
	v_exp_f32_e32 v94, v92
	v_sub_f32_e32 v92, v228, v246
	v_exp_f32_e32 v92, v92
	v_add_f32_e32 v95, v81, v91
	v_sub_f32_e32 v66, v66, v246
	v_add_f32_e32 v96, v94, v92
	v_add_f32_e32 v97, v95, v93
	v_exp_f32_e32 v93, v86
	v_sub_f32_e32 v86, v87, v246
	v_add_f32_e32 v97, v96, v97
	v_exp_f32_e32 v95, v86
	v_sub_f32_e32 v86, v88, v246
	v_sub_f32_e32 v87, v89, v246
	v_exp_f32_e32 v86, v86
	v_exp_f32_e32 v96, v87
	v_add_f32_e32 v87, v93, v95
	v_add_f32_e32 v88, v86, v96
	v_add_f32_e32 v89, v87, v97
	v_exp_f32_e32 v87, v82
	v_sub_f32_e32 v82, v83, v246
	v_add_f32_e32 v89, v88, v89
	v_exp_f32_e32 v97, v82
	v_sub_f32_e32 v82, v84, v246
	v_sub_f32_e32 v83, v85, v246
	v_exp_f32_e32 v82, v82
	v_exp_f32_e32 v88, v83
	v_add_f32_e32 v83, v87, v97
	v_add_f32_e32 v84, v82, v88
	v_add_f32_e32 v85, v83, v89
	v_exp_f32_e32 v83, v74
	v_sub_f32_e32 v74, v75, v246
	v_exp_f32_e32 v89, v74
	v_sub_f32_e32 v74, v76, v246
	v_add_f32_e32 v85, v84, v85
	v_exp_f32_e32 v76, v74
	v_sub_f32_e32 v74, v77, v246
	v_exp_f32_e32 v84, v74
	v_add_f32_e32 v77, v83, v89
	v_add_f32_e32 v74, v76, v84
	v_add_f32_e32 v75, v77, v85
	v_exp_f32_e32 v77, v70
	v_sub_f32_e32 v70, v71, v246
	v_exp_f32_e32 v85, v70
	v_sub_f32_e32 v70, v72, v246
	v_add_f32_e32 v185, v74, v75
	v_exp_f32_e32 v228, v70
	v_sub_f32_e32 v70, v73, v246
	v_exp_f32_e32 v184, v70
	v_add_f32_e32 v229, v77, v85
	v_cvt_pk_bf16_f32 v72, v91, v92
	v_cvt_pk_bf16_f32 v73, v95, v96
	v_add_f32_e32 v70, v228, v184
	v_add_f32_e32 v71, v229, v185
	v_exp_f32_e32 v185, v66
	v_sub_f32_e32 v66, v67, v246
	v_exp_f32_e32 v227, v66
	v_sub_f32_e32 v66, v68, v246
	v_add_f32_e32 v231, v70, v71
	v_exp_f32_e32 v232, v66
	v_sub_f32_e32 v66, v69, v246
	v_exp_f32_e32 v230, v66
	v_add_f32_e32 v233, v185, v227
	v_cvt_pk_bf16_f32 v68, v81, v94
	v_cvt_pk_bf16_f32 v69, v93, v86
	v_add_f32_e32 v66, v232, v230
	v_add_f32_e32 v67, v233, v231
	v_cvt_pk_bf16_f32 v70, v237, v188
	v_add_f32_e32 v66, v66, v67
	v_add_f32_e32 v224, v224, v66
	v_cvt_pk_bf16_f32 v66, v236, v78
	v_cvt_pk_bf16_f32 v67, v79, v90
	v_cvt_pk_bf16_f32 v71, v234, v80
	v_cvt_pk_bf16_f32 v74, v87, v82
	v_cvt_pk_bf16_f32 v75, v83, v76
	v_cvt_pk_bf16_f32 v76, v77, v228
	v_cvt_pk_bf16_f32 v77, v185, v232
	v_cvt_pk_bf16_f32 v78, v97, v88
	v_cvt_pk_bf16_f32 v79, v89, v84
	v_cvt_pk_bf16_f32 v80, v85, v184
	v_cvt_pk_bf16_f32 v81, v227, v230
	ds_read_b128 v[82:85], v221 offset:53312
	ds_read_b128 v[86:89], v221 offset:53344
	ds_read_b128 v[90:93], v221 offset:57920
	ds_read_b128 v[94:97], v221 offset:57952
	ds_read_b128 v[228:231], v221 offset:62528
	ds_read_b128 v[232:235], v221 offset:62560
	ds_read_b128 v[236:239], v225 offset:13888
	ds_read_b128 v[240:243], v225 offset:13920
	v_mfma_f32_32x32x16_bf16 v[50:65], v[166:169], v[66:69], v[50:65]
	v_mfma_f32_32x32x16_bf16 v[34:49], v[170:173], v[66:69], v[34:49]
	v_mfma_f32_32x32x16_bf16 v[18:33], v[174:177], v[66:69], v[18:33]
	v_mfma_f32_32x32x16_bf16 v[2:17], v[162:165], v[66:69], v[2:17]
	v_mfma_f32_32x32x16_bf16 v[50:65], v[150:153], v[74:77], v[50:65]
	v_mfma_f32_32x32x16_bf16 v[34:49], v[154:157], v[74:77], v[34:49]
	v_mfma_f32_32x32x16_bf16 v[18:33], v[158:161], v[74:77], v[18:33]
	v_mfma_f32_32x32x16_bf16 v[2:17], v[146:149], v[74:77], v[2:17]
	s_waitcnt lgkmcnt(7)
	v_mfma_f32_32x32x16_bf16 v[50:65], v[82:85], v[70:73], v[50:65]
	s_waitcnt lgkmcnt(5)
	v_mfma_f32_32x32x16_bf16 v[34:49], v[90:93], v[70:73], v[34:49]
	s_waitcnt lgkmcnt(3)
	v_mfma_f32_32x32x16_bf16 v[18:33], v[228:231], v[70:73], v[18:33]
	s_waitcnt lgkmcnt(1)
	v_mfma_f32_32x32x16_bf16 v[2:17], v[236:239], v[70:73], v[2:17]
	v_mfma_f32_32x32x16_bf16 v[50:65], v[86:89], v[78:81], v[50:65]
	v_mfma_f32_32x32x16_bf16 v[34:49], v[94:97], v[78:81], v[34:49]
	v_mfma_f32_32x32x16_bf16 v[18:33], v[232:235], v[78:81], v[18:33]
	s_waitcnt lgkmcnt(0)
	v_mfma_f32_32x32x16_bf16 v[2:17], v[240:243], v[78:81], v[2:17]
	s_cmp_ge_i32 s46, s26
	s_cbranch_scc1 .LBB0_1379
